# final grid barrier skipped after the last phase; gate/up compute_rowscale unrolled x11 with all loads in flight
# speedup vs baseline: 1.0067x; 1.0024x over previous
.LBB0_1081:
.LBB0_1082:
	s_mov_b64 s[2:3], s[84:85]
	s_mov_b32 s34, s72
	s_mov_b32 s6, s71
	s_load_dwordx2 s[12:13], s[2:3], 0x110
	v_mbcnt_lo_u32_b32 v0, -1, 0
	v_mbcnt_hi_u32_b32 v0, -1, v0
	s_getreg_b32 s2, hwreg(HW_REG_HW_ID, 0, 6)
	s_lshl_b32 s2, s2, 2
	s_and_b32 s2, s2, 0xfc
	s_add_i32 s2, s2, 0
	s_add_i32 s2, s2, 0x23400
	v_mov_b32_e32 v2, s2
	ds_read_b32 v2, v2
	v_and_b32_e32 v6, 1, v0
	s_ashr_i32 s7, s6, 31
	s_xor_b64 s[10:11], s[58:59], -1
	s_ashr_i32 s35, s34, 31
	s_waitcnt lgkmcnt(0)
	v_readfirstlane_b32 s2, v2
	v_cmp_eq_u32_e64 s[4:5], 0, v6
	s_mov_b64 s[8:9], s[6:7]
	v_lshl_add_u32 v2, s2, 6, v0
	v_ashrrev_i32_e32 v4, 1, v2
	v_ashrrev_i32_e32 v5, 31, v4
	v_lshlrev_b64 v[2:3], 7, v[4:5]
	v_lshl_add_u64 v[2:3], s[12:13], 0, v[2:3]
	v_lshlrev_b32_e32 v0, 6, v6
	v_lshl_add_u64 v[2:3], v[2:3], 0, v[0:1]
	s_mov_b64 s[2:3], 0x100000
	v_lshl_add_u64 v[2:3], v[2:3], 0, s[2:3]
	v_readlane_b32 s2, v255, 4
	s_nop 1
	v_lshl_add_u32 v0, v4, 2, s2
	s_cmp_eq_u32 s34, 0x100
	s_cbranch_scc0 .LBB0_1085
	s_mov_b32 s100, s8
	s_waitcnt lgkmcnt(0)
	s_ashr_i32 s2, s100, 31
	s_lshr_b32 s2, s2, 29
	s_add_i32 s2, s100, s2
	s_ashr_i32 s3, s2, 3
	s_and_b32 s2, s2, -8
	s_sub_i32 s2, s100, s2
	s_cmp_lt_i32 s2, 0
	s_cselect_b32 s14, s62, 0x160
	s_mul_i32 s2, s2, s14
	s_add_i32 s2, s2, s3
	s_mul_hi_i32 s3, s2, 0x2e8ba2e9
	s_lshr_b32 s14, s3, 31
	s_ashr_i32 s3, s3, 5
	s_add_i32 s3, s3, s14
	s_lshl_b32 s14, s3, 3
	s_sub_i32 s15, 0x80, s14
	s_min_i32 s15, s15, 8
	s_abs_i32 s15, s15
	v_cvt_f32_u32_e32 v4, s15
	s_sub_i32 s16, 0, s15
	s_mulk_i32 s3, 0xb0
	s_sub_i32 s2, s2, s3
	v_rcp_iflag_f32_e32 v4, v4
	s_ashr_i32 s3, s2, 31
	s_abs_i32 s2, s2
	v_mul_f32_e32 v4, 0x4f7ffffe, v4
	v_cvt_u32_f32_e32 v4, v4
	s_nop 0
	v_readfirstlane_b32 s17, v4
	s_mul_i32 s16, s16, s17
	s_mul_hi_u32 s16, s17, s16
	s_add_i32 s17, s17, s16
	s_mul_hi_u32 s16, s2, s17
	s_mul_i32 s16, s16, s15
	s_sub_i32 s2, s2, s16
	s_sub_i32 s16, s2, s15
	s_cmp_ge_u32 s2, s15
	s_cselect_b32 s2, s16, s2
	s_sub_i32 s16, s2, s15
	s_cmp_ge_u32 s2, s15
	s_cselect_b32 s2, s16, s2
	s_xor_b32 s2, s2, s3
	s_sub_i32 s2, s2, s3
	s_add_i32 s2, s14, s2
	s_ashr_i32 s3, s2, 31
	s_lshl_b64 s[2:3], s[2:3], 15
	v_lshl_add_u64 v[32:33], v[2:3], 0, s[2:3]
	global_load_dwordx4 v[20:23], v[32:33], off
	global_load_dwordx4 v[24:27], v[32:33], off offset:16
	global_load_dwordx4 v[28:31], v[32:33], off offset:32
	s_nop 0
	global_load_dwordx4 v[32:35], v[32:33], off offset:48
	s_add_i32 s100, s100, 0x100
	s_ashr_i32 s2, s100, 31
	s_lshr_b32 s2, s2, 29
	s_add_i32 s2, s100, s2
	s_ashr_i32 s3, s2, 3
	s_and_b32 s2, s2, -8
	s_sub_i32 s2, s100, s2
	s_cmp_lt_i32 s2, 0
	s_cselect_b32 s14, s62, 0x160
	s_mul_i32 s2, s2, s14
	s_add_i32 s2, s2, s3
	s_mul_hi_i32 s3, s2, 0x2e8ba2e9
	s_lshr_b32 s14, s3, 31
	s_ashr_i32 s3, s3, 5
	s_add_i32 s3, s3, s14
	s_lshl_b32 s14, s3, 3
	s_sub_i32 s15, 0x80, s14
	s_min_i32 s15, s15, 8
	s_abs_i32 s15, s15
	v_cvt_f32_u32_e32 v4, s15
	s_sub_i32 s16, 0, s15
	s_mulk_i32 s3, 0xb0
	s_sub_i32 s2, s2, s3
	v_rcp_iflag_f32_e32 v4, v4
	s_ashr_i32 s3, s2, 31
	s_abs_i32 s2, s2
	v_mul_f32_e32 v4, 0x4f7ffffe, v4
	v_cvt_u32_f32_e32 v4, v4
	s_nop 0
	v_readfirstlane_b32 s17, v4
	s_mul_i32 s16, s16, s17
	s_mul_hi_u32 s16, s17, s16
	s_add_i32 s17, s17, s16
	s_mul_hi_u32 s16, s2, s17
	s_mul_i32 s16, s16, s15
	s_sub_i32 s2, s2, s16
	s_sub_i32 s16, s2, s15
	s_cmp_ge_u32 s2, s15
	s_cselect_b32 s2, s16, s2
	s_sub_i32 s16, s2, s15
	s_cmp_ge_u32 s2, s15
	s_cselect_b32 s2, s16, s2
	s_xor_b32 s2, s2, s3
	s_sub_i32 s2, s2, s3
	s_add_i32 s2, s14, s2
	s_ashr_i32 s3, s2, 31
	s_lshl_b64 s[2:3], s[2:3], 15
	v_lshl_add_u64 v[48:49], v[2:3], 0, s[2:3]
	global_load_dwordx4 v[36:39], v[48:49], off
	global_load_dwordx4 v[40:43], v[48:49], off offset:16
	global_load_dwordx4 v[44:47], v[48:49], off offset:32
	s_nop 0
	global_load_dwordx4 v[48:51], v[48:49], off offset:48
	s_add_i32 s100, s100, 0x100
	s_ashr_i32 s2, s100, 31
	s_lshr_b32 s2, s2, 29
	s_add_i32 s2, s100, s2
	s_ashr_i32 s3, s2, 3
	s_and_b32 s2, s2, -8
	s_sub_i32 s2, s100, s2
	s_cmp_lt_i32 s2, 0
	s_cselect_b32 s14, s62, 0x160
	s_mul_i32 s2, s2, s14
	s_add_i32 s2, s2, s3
	s_mul_hi_i32 s3, s2, 0x2e8ba2e9
	s_lshr_b32 s14, s3, 31
	s_ashr_i32 s3, s3, 5
	s_add_i32 s3, s3, s14
	s_lshl_b32 s14, s3, 3
	s_sub_i32 s15, 0x80, s14
	s_min_i32 s15, s15, 8
	s_abs_i32 s15, s15
	v_cvt_f32_u32_e32 v4, s15
	s_sub_i32 s16, 0, s15
	s_mulk_i32 s3, 0xb0
	s_sub_i32 s2, s2, s3
	v_rcp_iflag_f32_e32 v4, v4
	s_ashr_i32 s3, s2, 31
	s_abs_i32 s2, s2
	v_mul_f32_e32 v4, 0x4f7ffffe, v4
	v_cvt_u32_f32_e32 v4, v4
	s_nop 0
	v_readfirstlane_b32 s17, v4
	s_mul_i32 s16, s16, s17
	s_mul_hi_u32 s16, s17, s16
	s_add_i32 s17, s17, s16
	s_mul_hi_u32 s16, s2, s17
	s_mul_i32 s16, s16, s15
	s_sub_i32 s2, s2, s16
	s_sub_i32 s16, s2, s15
	s_cmp_ge_u32 s2, s15
	s_cselect_b32 s2, s16, s2
	s_sub_i32 s16, s2, s15
	s_cmp_ge_u32 s2, s15
	s_cselect_b32 s2, s16, s2
	s_xor_b32 s2, s2, s3
	s_sub_i32 s2, s2, s3
	s_add_i32 s2, s14, s2
	s_ashr_i32 s3, s2, 31
	s_lshl_b64 s[2:3], s[2:3], 15
	v_lshl_add_u64 v[64:65], v[2:3], 0, s[2:3]
	global_load_dwordx4 v[52:55], v[64:65], off
	global_load_dwordx4 v[56:59], v[64:65], off offset:16
	global_load_dwordx4 v[60:63], v[64:65], off offset:32
	s_nop 0
	global_load_dwordx4 v[64:67], v[64:65], off offset:48
	s_add_i32 s100, s100, 0x100
	s_ashr_i32 s2, s100, 31
	s_lshr_b32 s2, s2, 29
	s_add_i32 s2, s100, s2
	s_ashr_i32 s3, s2, 3
	s_and_b32 s2, s2, -8
	s_sub_i32 s2, s100, s2
	s_cmp_lt_i32 s2, 0
	s_cselect_b32 s14, s62, 0x160
	s_mul_i32 s2, s2, s14
	s_add_i32 s2, s2, s3
	s_mul_hi_i32 s3, s2, 0x2e8ba2e9
	s_lshr_b32 s14, s3, 31
	s_ashr_i32 s3, s3, 5
	s_add_i32 s3, s3, s14
	s_lshl_b32 s14, s3, 3
	s_sub_i32 s15, 0x80, s14
	s_min_i32 s15, s15, 8
	s_abs_i32 s15, s15
	v_cvt_f32_u32_e32 v4, s15
	s_sub_i32 s16, 0, s15
	s_mulk_i32 s3, 0xb0
	s_sub_i32 s2, s2, s3
	v_rcp_iflag_f32_e32 v4, v4
	s_ashr_i32 s3, s2, 31
	s_abs_i32 s2, s2
	v_mul_f32_e32 v4, 0x4f7ffffe, v4
	v_cvt_u32_f32_e32 v4, v4
	s_nop 0
	v_readfirstlane_b32 s17, v4
	s_mul_i32 s16, s16, s17
	s_mul_hi_u32 s16, s17, s16
	s_add_i32 s17, s17, s16
	s_mul_hi_u32 s16, s2, s17
	s_mul_i32 s16, s16, s15
	s_sub_i32 s2, s2, s16
	s_sub_i32 s16, s2, s15
	s_cmp_ge_u32 s2, s15
	s_cselect_b32 s2, s16, s2
	s_sub_i32 s16, s2, s15
	s_cmp_ge_u32 s2, s15
	s_cselect_b32 s2, s16, s2
	s_xor_b32 s2, s2, s3
	s_sub_i32 s2, s2, s3
	s_add_i32 s2, s14, s2
	s_ashr_i32 s3, s2, 31
	s_lshl_b64 s[2:3], s[2:3], 15
	v_lshl_add_u64 v[80:81], v[2:3], 0, s[2:3]
	global_load_dwordx4 v[68:71], v[80:81], off
	global_load_dwordx4 v[72:75], v[80:81], off offset:16
	global_load_dwordx4 v[76:79], v[80:81], off offset:32
	s_nop 0
	global_load_dwordx4 v[80:83], v[80:81], off offset:48
	s_add_i32 s100, s100, 0x100
	s_ashr_i32 s2, s100, 31
	s_lshr_b32 s2, s2, 29
	s_add_i32 s2, s100, s2
	s_ashr_i32 s3, s2, 3
	s_and_b32 s2, s2, -8
	s_sub_i32 s2, s100, s2
	s_cmp_lt_i32 s2, 0
	s_cselect_b32 s14, s62, 0x160
	s_mul_i32 s2, s2, s14
	s_add_i32 s2, s2, s3
	s_mul_hi_i32 s3, s2, 0x2e8ba2e9
	s_lshr_b32 s14, s3, 31
	s_ashr_i32 s3, s3, 5
	s_add_i32 s3, s3, s14
	s_lshl_b32 s14, s3, 3
	s_sub_i32 s15, 0x80, s14
	s_min_i32 s15, s15, 8
	s_abs_i32 s15, s15
	v_cvt_f32_u32_e32 v4, s15
	s_sub_i32 s16, 0, s15
	s_mulk_i32 s3, 0xb0
	s_sub_i32 s2, s2, s3
	v_rcp_iflag_f32_e32 v4, v4
	s_ashr_i32 s3, s2, 31
	s_abs_i32 s2, s2
	v_mul_f32_e32 v4, 0x4f7ffffe, v4
	v_cvt_u32_f32_e32 v4, v4
	s_nop 0
	v_readfirstlane_b32 s17, v4
	s_mul_i32 s16, s16, s17
	s_mul_hi_u32 s16, s17, s16
	s_add_i32 s17, s17, s16
	s_mul_hi_u32 s16, s2, s17
	s_mul_i32 s16, s16, s15
	s_sub_i32 s2, s2, s16
	s_sub_i32 s16, s2, s15
	s_cmp_ge_u32 s2, s15
	s_cselect_b32 s2, s16, s2
	s_sub_i32 s16, s2, s15
	s_cmp_ge_u32 s2, s15
	s_cselect_b32 s2, s16, s2
	s_xor_b32 s2, s2, s3
	s_sub_i32 s2, s2, s3
	s_add_i32 s2, s14, s2
	s_ashr_i32 s3, s2, 31
	s_lshl_b64 s[2:3], s[2:3], 15
	v_lshl_add_u64 v[96:97], v[2:3], 0, s[2:3]
	global_load_dwordx4 v[84:87], v[96:97], off
	global_load_dwordx4 v[88:91], v[96:97], off offset:16
	global_load_dwordx4 v[92:95], v[96:97], off offset:32
	s_nop 0
	global_load_dwordx4 v[96:99], v[96:97], off offset:48
	s_add_i32 s100, s100, 0x100
	s_ashr_i32 s2, s100, 31
	s_lshr_b32 s2, s2, 29
	s_add_i32 s2, s100, s2
	s_ashr_i32 s3, s2, 3
	s_and_b32 s2, s2, -8
	s_sub_i32 s2, s100, s2
	s_cmp_lt_i32 s2, 0
	s_cselect_b32 s14, s62, 0x160
	s_mul_i32 s2, s2, s14
	s_add_i32 s2, s2, s3
	s_mul_hi_i32 s3, s2, 0x2e8ba2e9
	s_lshr_b32 s14, s3, 31
	s_ashr_i32 s3, s3, 5
	s_add_i32 s3, s3, s14
	s_lshl_b32 s14, s3, 3
	s_sub_i32 s15, 0x80, s14
	s_min_i32 s15, s15, 8
	s_abs_i32 s15, s15
	v_cvt_f32_u32_e32 v4, s15
	s_sub_i32 s16, 0, s15
	s_mulk_i32 s3, 0xb0
	s_sub_i32 s2, s2, s3
	v_rcp_iflag_f32_e32 v4, v4
	s_ashr_i32 s3, s2, 31
	s_abs_i32 s2, s2
	v_mul_f32_e32 v4, 0x4f7ffffe, v4
	v_cvt_u32_f32_e32 v4, v4
	s_nop 0
	v_readfirstlane_b32 s17, v4
	s_mul_i32 s16, s16, s17
	s_mul_hi_u32 s16, s17, s16
	s_add_i32 s17, s17, s16
	s_mul_hi_u32 s16, s2, s17
	s_mul_i32 s16, s16, s15
	s_sub_i32 s2, s2, s16
	s_sub_i32 s16, s2, s15
	s_cmp_ge_u32 s2, s15
	s_cselect_b32 s2, s16, s2
	s_sub_i32 s16, s2, s15
	s_cmp_ge_u32 s2, s15
	s_cselect_b32 s2, s16, s2
	s_xor_b32 s2, s2, s3
	s_sub_i32 s2, s2, s3
	s_add_i32 s2, s14, s2
	s_ashr_i32 s3, s2, 31
	s_lshl_b64 s[2:3], s[2:3], 15
	v_lshl_add_u64 v[112:113], v[2:3], 0, s[2:3]
	global_load_dwordx4 v[100:103], v[112:113], off
	global_load_dwordx4 v[104:107], v[112:113], off offset:16
	global_load_dwordx4 v[108:111], v[112:113], off offset:32
	s_nop 0
	global_load_dwordx4 v[112:115], v[112:113], off offset:48
	s_add_i32 s100, s100, 0x100
	s_ashr_i32 s2, s100, 31
	s_lshr_b32 s2, s2, 29
	s_add_i32 s2, s100, s2
	s_ashr_i32 s3, s2, 3
	s_and_b32 s2, s2, -8
	s_sub_i32 s2, s100, s2
	s_cmp_lt_i32 s2, 0
	s_cselect_b32 s14, s62, 0x160
	s_mul_i32 s2, s2, s14
	s_add_i32 s2, s2, s3
	s_mul_hi_i32 s3, s2, 0x2e8ba2e9
	s_lshr_b32 s14, s3, 31
	s_ashr_i32 s3, s3, 5
	s_add_i32 s3, s3, s14
	s_lshl_b32 s14, s3, 3
	s_sub_i32 s15, 0x80, s14
	s_min_i32 s15, s15, 8
	s_abs_i32 s15, s15
	v_cvt_f32_u32_e32 v4, s15
	s_sub_i32 s16, 0, s15
	s_mulk_i32 s3, 0xb0
	s_sub_i32 s2, s2, s3
	v_rcp_iflag_f32_e32 v4, v4
	s_ashr_i32 s3, s2, 31
	s_abs_i32 s2, s2
	v_mul_f32_e32 v4, 0x4f7ffffe, v4
	v_cvt_u32_f32_e32 v4, v4
	s_nop 0
	v_readfirstlane_b32 s17, v4
	s_mul_i32 s16, s16, s17
	s_mul_hi_u32 s16, s17, s16
	s_add_i32 s17, s17, s16
	s_mul_hi_u32 s16, s2, s17
	s_mul_i32 s16, s16, s15
	s_sub_i32 s2, s2, s16
	s_sub_i32 s16, s2, s15
	s_cmp_ge_u32 s2, s15
	s_cselect_b32 s2, s16, s2
	s_sub_i32 s16, s2, s15
	s_cmp_ge_u32 s2, s15
	s_cselect_b32 s2, s16, s2
	s_xor_b32 s2, s2, s3
	s_sub_i32 s2, s2, s3
	s_add_i32 s2, s14, s2
	s_ashr_i32 s3, s2, 31
	s_lshl_b64 s[2:3], s[2:3], 15
	v_lshl_add_u64 v[128:129], v[2:3], 0, s[2:3]
	global_load_dwordx4 v[116:119], v[128:129], off
	global_load_dwordx4 v[120:123], v[128:129], off offset:16
	global_load_dwordx4 v[124:127], v[128:129], off offset:32
	s_nop 0
	global_load_dwordx4 v[128:131], v[128:129], off offset:48
	s_add_i32 s100, s100, 0x100
	s_ashr_i32 s2, s100, 31
	s_lshr_b32 s2, s2, 29
	s_add_i32 s2, s100, s2
	s_ashr_i32 s3, s2, 3
	s_and_b32 s2, s2, -8
	s_sub_i32 s2, s100, s2
	s_cmp_lt_i32 s2, 0
	s_cselect_b32 s14, s62, 0x160
	s_mul_i32 s2, s2, s14
	s_add_i32 s2, s2, s3
	s_mul_hi_i32 s3, s2, 0x2e8ba2e9
	s_lshr_b32 s14, s3, 31
	s_ashr_i32 s3, s3, 5
	s_add_i32 s3, s3, s14
	s_lshl_b32 s14, s3, 3
	s_sub_i32 s15, 0x80, s14
	s_min_i32 s15, s15, 8
	s_abs_i32 s15, s15
	v_cvt_f32_u32_e32 v4, s15
	s_sub_i32 s16, 0, s15
	s_mulk_i32 s3, 0xb0
	s_sub_i32 s2, s2, s3
	v_rcp_iflag_f32_e32 v4, v4
	s_ashr_i32 s3, s2, 31
	s_abs_i32 s2, s2
	v_mul_f32_e32 v4, 0x4f7ffffe, v4
	v_cvt_u32_f32_e32 v4, v4
	s_nop 0
	v_readfirstlane_b32 s17, v4
	s_mul_i32 s16, s16, s17
	s_mul_hi_u32 s16, s17, s16
	s_add_i32 s17, s17, s16
	s_mul_hi_u32 s16, s2, s17
	s_mul_i32 s16, s16, s15
	s_sub_i32 s2, s2, s16
	s_sub_i32 s16, s2, s15
	s_cmp_ge_u32 s2, s15
	s_cselect_b32 s2, s16, s2
	s_sub_i32 s16, s2, s15
	s_cmp_ge_u32 s2, s15
	s_cselect_b32 s2, s16, s2
	s_xor_b32 s2, s2, s3
	s_sub_i32 s2, s2, s3
	s_add_i32 s2, s14, s2
	s_ashr_i32 s3, s2, 31
	s_lshl_b64 s[2:3], s[2:3], 15
	v_lshl_add_u64 v[144:145], v[2:3], 0, s[2:3]
	global_load_dwordx4 v[132:135], v[144:145], off
	global_load_dwordx4 v[136:139], v[144:145], off offset:16
	global_load_dwordx4 v[140:143], v[144:145], off offset:32
	s_nop 0
	global_load_dwordx4 v[144:147], v[144:145], off offset:48
	s_add_i32 s100, s100, 0x100
	s_ashr_i32 s2, s100, 31
	s_lshr_b32 s2, s2, 29
	s_add_i32 s2, s100, s2
	s_ashr_i32 s3, s2, 3
	s_and_b32 s2, s2, -8
	s_sub_i32 s2, s100, s2
	s_cmp_lt_i32 s2, 0
	s_cselect_b32 s14, s62, 0x160
	s_mul_i32 s2, s2, s14
	s_add_i32 s2, s2, s3
	s_mul_hi_i32 s3, s2, 0x2e8ba2e9
	s_lshr_b32 s14, s3, 31
	s_ashr_i32 s3, s3, 5
	s_add_i32 s3, s3, s14
	s_lshl_b32 s14, s3, 3
	s_sub_i32 s15, 0x80, s14
	s_min_i32 s15, s15, 8
	s_abs_i32 s15, s15
	v_cvt_f32_u32_e32 v4, s15
	s_sub_i32 s16, 0, s15
	s_mulk_i32 s3, 0xb0
	s_sub_i32 s2, s2, s3
	v_rcp_iflag_f32_e32 v4, v4
	s_ashr_i32 s3, s2, 31
	s_abs_i32 s2, s2
	v_mul_f32_e32 v4, 0x4f7ffffe, v4
	v_cvt_u32_f32_e32 v4, v4
	s_nop 0
	v_readfirstlane_b32 s17, v4
	s_mul_i32 s16, s16, s17
	s_mul_hi_u32 s16, s17, s16
	s_add_i32 s17, s17, s16
	s_mul_hi_u32 s16, s2, s17
	s_mul_i32 s16, s16, s15
	s_sub_i32 s2, s2, s16
	s_sub_i32 s16, s2, s15
	s_cmp_ge_u32 s2, s15
	s_cselect_b32 s2, s16, s2
	s_sub_i32 s16, s2, s15
	s_cmp_ge_u32 s2, s15
	s_cselect_b32 s2, s16, s2
	s_xor_b32 s2, s2, s3
	s_sub_i32 s2, s2, s3
	s_add_i32 s2, s14, s2
	s_ashr_i32 s3, s2, 31
	s_lshl_b64 s[2:3], s[2:3], 15
	v_lshl_add_u64 v[160:161], v[2:3], 0, s[2:3]
	global_load_dwordx4 v[148:151], v[160:161], off
	global_load_dwordx4 v[152:155], v[160:161], off offset:16
	global_load_dwordx4 v[156:159], v[160:161], off offset:32
	s_nop 0
	global_load_dwordx4 v[160:163], v[160:161], off offset:48
	s_add_i32 s100, s100, 0x100
	s_ashr_i32 s2, s100, 31
	s_lshr_b32 s2, s2, 29
	s_add_i32 s2, s100, s2
	s_ashr_i32 s3, s2, 3
	s_and_b32 s2, s2, -8
	s_sub_i32 s2, s100, s2
	s_cmp_lt_i32 s2, 0
	s_cselect_b32 s14, s62, 0x160
	s_mul_i32 s2, s2, s14
	s_add_i32 s2, s2, s3
	s_mul_hi_i32 s3, s2, 0x2e8ba2e9
	s_lshr_b32 s14, s3, 31
	s_ashr_i32 s3, s3, 5
	s_add_i32 s3, s3, s14
	s_lshl_b32 s14, s3, 3
	s_sub_i32 s15, 0x80, s14
	s_min_i32 s15, s15, 8
	s_abs_i32 s15, s15
	v_cvt_f32_u32_e32 v4, s15
	s_sub_i32 s16, 0, s15
	s_mulk_i32 s3, 0xb0
	s_sub_i32 s2, s2, s3
	v_rcp_iflag_f32_e32 v4, v4
	s_ashr_i32 s3, s2, 31
	s_abs_i32 s2, s2
	v_mul_f32_e32 v4, 0x4f7ffffe, v4
	v_cvt_u32_f32_e32 v4, v4
	s_nop 0
	v_readfirstlane_b32 s17, v4
	s_mul_i32 s16, s16, s17
	s_mul_hi_u32 s16, s17, s16
	s_add_i32 s17, s17, s16
	s_mul_hi_u32 s16, s2, s17
	s_mul_i32 s16, s16, s15
	s_sub_i32 s2, s2, s16
	s_sub_i32 s16, s2, s15
	s_cmp_ge_u32 s2, s15
	s_cselect_b32 s2, s16, s2
	s_sub_i32 s16, s2, s15
	s_cmp_ge_u32 s2, s15
	s_cselect_b32 s2, s16, s2
	s_xor_b32 s2, s2, s3
	s_sub_i32 s2, s2, s3
	s_add_i32 s2, s14, s2
	s_ashr_i32 s3, s2, 31
	s_lshl_b64 s[2:3], s[2:3], 15
	v_lshl_add_u64 v[192:193], v[2:3], 0, s[2:3]
	global_load_dwordx4 v[180:183], v[192:193], off
	global_load_dwordx4 v[184:187], v[192:193], off offset:16
	global_load_dwordx4 v[188:191], v[192:193], off offset:32
	s_nop 0
	global_load_dwordx4 v[192:195], v[192:193], off offset:48
	s_add_i32 s100, s100, 0x100
	s_ashr_i32 s2, s100, 31
	s_lshr_b32 s2, s2, 29
	s_add_i32 s2, s100, s2
	s_ashr_i32 s3, s2, 3
	s_and_b32 s2, s2, -8
	s_sub_i32 s2, s100, s2
	s_cmp_lt_i32 s2, 0
	s_cselect_b32 s14, s62, 0x160
	s_mul_i32 s2, s2, s14
	s_add_i32 s2, s2, s3
	s_mul_hi_i32 s3, s2, 0x2e8ba2e9
	s_lshr_b32 s14, s3, 31
	s_ashr_i32 s3, s3, 5
	s_add_i32 s3, s3, s14
	s_lshl_b32 s14, s3, 3
	s_sub_i32 s15, 0x80, s14
	s_min_i32 s15, s15, 8
	s_abs_i32 s15, s15
	v_cvt_f32_u32_e32 v4, s15
	s_sub_i32 s16, 0, s15
	s_mulk_i32 s3, 0xb0
	s_sub_i32 s2, s2, s3
	v_rcp_iflag_f32_e32 v4, v4
	s_ashr_i32 s3, s2, 31
	s_abs_i32 s2, s2
	v_mul_f32_e32 v4, 0x4f7ffffe, v4
	v_cvt_u32_f32_e32 v4, v4
	s_nop 0
	v_readfirstlane_b32 s17, v4
	s_mul_i32 s16, s16, s17
	s_mul_hi_u32 s16, s17, s16
	s_add_i32 s17, s17, s16
	s_mul_hi_u32 s16, s2, s17
	s_mul_i32 s16, s16, s15
	s_sub_i32 s2, s2, s16
	s_sub_i32 s16, s2, s15
	s_cmp_ge_u32 s2, s15
	s_cselect_b32 s2, s16, s2
	s_sub_i32 s16, s2, s15
	s_cmp_ge_u32 s2, s15
	s_cselect_b32 s2, s16, s2
	s_xor_b32 s2, s2, s3
	s_sub_i32 s2, s2, s3
	s_add_i32 s2, s14, s2
	s_ashr_i32 s3, s2, 31
	s_lshl_b64 s[2:3], s[2:3], 15
	v_lshl_add_u64 v[208:209], v[2:3], 0, s[2:3]
	global_load_dwordx4 v[196:199], v[208:209], off
	global_load_dwordx4 v[200:203], v[208:209], off offset:16
	global_load_dwordx4 v[204:207], v[208:209], off offset:32
	s_nop 0
	global_load_dwordx4 v[208:211], v[208:209], off offset:48
	s_waitcnt vmcnt(40)
	v_add_f32_e32 v20, v20, v21
	v_add_f32_e32 v21, v22, v23
	v_add_f32_e32 v22, v24, v25
	v_add_f32_e32 v23, v26, v27
	v_add_f32_e32 v24, v28, v29
	v_add_f32_e32 v25, v30, v31
	v_add_f32_e32 v20, v20, v21
	v_add_f32_e32 v21, v22, v23
	v_add_f32_e32 v26, v32, v33
	v_add_f32_e32 v27, v34, v35
	v_add_f32_e32 v22, v24, v25
	v_add_f32_e32 v20, v20, v21
	v_add_f32_e32 v20, v20, v22
	v_add_f32_e32 v21, v26, v27
	v_add_f32_e32 v20, v20, v21
	ds_swizzle_b32 v21, v20 offset:swizzle(SWAP,1)
	s_waitcnt vmcnt(36)
	v_add_f32_e32 v36, v36, v37
	v_add_f32_e32 v37, v38, v39
	v_add_f32_e32 v38, v40, v41
	v_add_f32_e32 v39, v42, v43
	v_add_f32_e32 v40, v44, v45
	v_add_f32_e32 v41, v46, v47
	v_add_f32_e32 v36, v36, v37
	v_add_f32_e32 v37, v38, v39
	v_add_f32_e32 v42, v48, v49
	v_add_f32_e32 v43, v50, v51
	v_add_f32_e32 v38, v40, v41
	v_add_f32_e32 v36, v36, v37
	v_add_f32_e32 v36, v36, v38
	v_add_f32_e32 v37, v42, v43
	v_add_f32_e32 v36, v36, v37
	ds_swizzle_b32 v37, v36 offset:swizzle(SWAP,1)
	s_waitcnt vmcnt(32)
	v_add_f32_e32 v52, v52, v53
	v_add_f32_e32 v53, v54, v55
	v_add_f32_e32 v54, v56, v57
	v_add_f32_e32 v55, v58, v59
	v_add_f32_e32 v56, v60, v61
	v_add_f32_e32 v57, v62, v63
	v_add_f32_e32 v52, v52, v53
	v_add_f32_e32 v53, v54, v55
	v_add_f32_e32 v58, v64, v65
	v_add_f32_e32 v59, v66, v67
	v_add_f32_e32 v54, v56, v57
	v_add_f32_e32 v52, v52, v53
	v_add_f32_e32 v52, v52, v54
	v_add_f32_e32 v53, v58, v59
	v_add_f32_e32 v52, v52, v53
	ds_swizzle_b32 v53, v52 offset:swizzle(SWAP,1)
	s_waitcnt vmcnt(28)
	v_add_f32_e32 v68, v68, v69
	v_add_f32_e32 v69, v70, v71
	v_add_f32_e32 v70, v72, v73
	v_add_f32_e32 v71, v74, v75
	v_add_f32_e32 v72, v76, v77
	v_add_f32_e32 v73, v78, v79
	v_add_f32_e32 v68, v68, v69
	v_add_f32_e32 v69, v70, v71
	v_add_f32_e32 v74, v80, v81
	v_add_f32_e32 v75, v82, v83
	v_add_f32_e32 v70, v72, v73
	v_add_f32_e32 v68, v68, v69
	v_add_f32_e32 v68, v68, v70
	v_add_f32_e32 v69, v74, v75
	v_add_f32_e32 v68, v68, v69
	ds_swizzle_b32 v69, v68 offset:swizzle(SWAP,1)
	s_waitcnt vmcnt(24)
	v_add_f32_e32 v84, v84, v85
	v_add_f32_e32 v85, v86, v87
	v_add_f32_e32 v86, v88, v89
	v_add_f32_e32 v87, v90, v91
	v_add_f32_e32 v88, v92, v93
	v_add_f32_e32 v89, v94, v95
	v_add_f32_e32 v84, v84, v85
	v_add_f32_e32 v85, v86, v87
	v_add_f32_e32 v90, v96, v97
	v_add_f32_e32 v91, v98, v99
	v_add_f32_e32 v86, v88, v89
	v_add_f32_e32 v84, v84, v85
	v_add_f32_e32 v84, v84, v86
	v_add_f32_e32 v85, v90, v91
	v_add_f32_e32 v84, v84, v85
	ds_swizzle_b32 v85, v84 offset:swizzle(SWAP,1)
	s_waitcnt vmcnt(20)
	v_add_f32_e32 v100, v100, v101
	v_add_f32_e32 v101, v102, v103
	v_add_f32_e32 v102, v104, v105
	v_add_f32_e32 v103, v106, v107
	v_add_f32_e32 v104, v108, v109
	v_add_f32_e32 v105, v110, v111
	v_add_f32_e32 v100, v100, v101
	v_add_f32_e32 v101, v102, v103
	v_add_f32_e32 v106, v112, v113
	v_add_f32_e32 v107, v114, v115
	v_add_f32_e32 v102, v104, v105
	v_add_f32_e32 v100, v100, v101
	v_add_f32_e32 v100, v100, v102
	v_add_f32_e32 v101, v106, v107
	v_add_f32_e32 v100, v100, v101
	ds_swizzle_b32 v101, v100 offset:swizzle(SWAP,1)
	s_waitcnt vmcnt(16)
	v_add_f32_e32 v116, v116, v117
	v_add_f32_e32 v117, v118, v119
	v_add_f32_e32 v118, v120, v121
	v_add_f32_e32 v119, v122, v123
	v_add_f32_e32 v120, v124, v125
	v_add_f32_e32 v121, v126, v127
	v_add_f32_e32 v116, v116, v117
	v_add_f32_e32 v117, v118, v119
	v_add_f32_e32 v122, v128, v129
	v_add_f32_e32 v123, v130, v131
	v_add_f32_e32 v118, v120, v121
	v_add_f32_e32 v116, v116, v117
	v_add_f32_e32 v116, v116, v118
	v_add_f32_e32 v117, v122, v123
	v_add_f32_e32 v116, v116, v117
	ds_swizzle_b32 v117, v116 offset:swizzle(SWAP,1)
	s_waitcnt vmcnt(12)
	v_add_f32_e32 v132, v132, v133
	v_add_f32_e32 v133, v134, v135
	v_add_f32_e32 v134, v136, v137
	v_add_f32_e32 v135, v138, v139
	v_add_f32_e32 v136, v140, v141
	v_add_f32_e32 v137, v142, v143
	v_add_f32_e32 v132, v132, v133
	v_add_f32_e32 v133, v134, v135
	v_add_f32_e32 v138, v144, v145
	v_add_f32_e32 v139, v146, v147
	v_add_f32_e32 v134, v136, v137
	v_add_f32_e32 v132, v132, v133
	v_add_f32_e32 v132, v132, v134
	v_add_f32_e32 v133, v138, v139
	v_add_f32_e32 v132, v132, v133
	ds_swizzle_b32 v133, v132 offset:swizzle(SWAP,1)
	s_waitcnt vmcnt(8)
	v_add_f32_e32 v148, v148, v149
	v_add_f32_e32 v149, v150, v151
	v_add_f32_e32 v150, v152, v153
	v_add_f32_e32 v151, v154, v155
	v_add_f32_e32 v152, v156, v157
	v_add_f32_e32 v153, v158, v159
	v_add_f32_e32 v148, v148, v149
	v_add_f32_e32 v149, v150, v151
	v_add_f32_e32 v154, v160, v161
	v_add_f32_e32 v155, v162, v163
	v_add_f32_e32 v150, v152, v153
	v_add_f32_e32 v148, v148, v149
	v_add_f32_e32 v148, v148, v150
	v_add_f32_e32 v149, v154, v155
	v_add_f32_e32 v148, v148, v149
	ds_swizzle_b32 v149, v148 offset:swizzle(SWAP,1)
	s_waitcnt vmcnt(4)
	v_add_f32_e32 v180, v180, v181
	v_add_f32_e32 v181, v182, v183
	v_add_f32_e32 v182, v184, v185
	v_add_f32_e32 v183, v186, v187
	v_add_f32_e32 v184, v188, v189
	v_add_f32_e32 v185, v190, v191
	v_add_f32_e32 v180, v180, v181
	v_add_f32_e32 v181, v182, v183
	v_add_f32_e32 v186, v192, v193
	v_add_f32_e32 v187, v194, v195
	v_add_f32_e32 v182, v184, v185
	v_add_f32_e32 v180, v180, v181
	v_add_f32_e32 v180, v180, v182
	v_add_f32_e32 v181, v186, v187
	v_add_f32_e32 v180, v180, v181
	ds_swizzle_b32 v181, v180 offset:swizzle(SWAP,1)
	s_waitcnt vmcnt(0)
	v_add_f32_e32 v196, v196, v197
	v_add_f32_e32 v197, v198, v199
	v_add_f32_e32 v198, v200, v201
	v_add_f32_e32 v199, v202, v203
	v_add_f32_e32 v200, v204, v205
	v_add_f32_e32 v201, v206, v207
	v_add_f32_e32 v196, v196, v197
	v_add_f32_e32 v197, v198, v199
	v_add_f32_e32 v202, v208, v209
	v_add_f32_e32 v203, v210, v211
	v_add_f32_e32 v198, v200, v201
	v_add_f32_e32 v196, v196, v197
	v_add_f32_e32 v196, v196, v198
	v_add_f32_e32 v197, v202, v203
	v_add_f32_e32 v196, v196, v197
	ds_swizzle_b32 v197, v196 offset:swizzle(SWAP,1)
	s_and_saveexec_b64 s[14:15], s[4:5]
	s_cbranch_execz .Lrs_skipw
	s_waitcnt lgkmcnt(0)
	v_add_f32_e32 v20, v20, v21
	v_fmamk_f32 v20, v20, 0x3a800000, v220
	v_mul_f32_e32 v21, 0x4b800000, v20
	v_cmp_gt_f32_e32 vcc, s33, v20
	s_nop 1
	v_cndmask_b32_e32 v20, v20, v21, vcc
	v_rsq_f32_e32 v20, v20
	s_nop 0
	v_mul_f32_e32 v21, 0x45800000, v20
	v_cndmask_b32_e32 v20, v20, v21, vcc
	ds_write_b32 v0, v20
	v_add_f32_e32 v36, v36, v37
	v_fmamk_f32 v36, v36, 0x3a800000, v220
	v_mul_f32_e32 v37, 0x4b800000, v36
	v_cmp_gt_f32_e32 vcc, s33, v36
	s_nop 1
	v_cndmask_b32_e32 v36, v36, v37, vcc
	v_rsq_f32_e32 v36, v36
	s_nop 0
	v_mul_f32_e32 v37, 0x45800000, v36
	v_cndmask_b32_e32 v36, v36, v37, vcc
	ds_write_b32 v0, v36 offset:1024
	v_add_f32_e32 v52, v52, v53
	v_fmamk_f32 v52, v52, 0x3a800000, v220
	v_mul_f32_e32 v53, 0x4b800000, v52
	v_cmp_gt_f32_e32 vcc, s33, v52
	s_nop 1
	v_cndmask_b32_e32 v52, v52, v53, vcc
	v_rsq_f32_e32 v52, v52
	s_nop 0
	v_mul_f32_e32 v53, 0x45800000, v52
	v_cndmask_b32_e32 v52, v52, v53, vcc
	ds_write_b32 v0, v52 offset:2048
	v_add_f32_e32 v68, v68, v69
	v_fmamk_f32 v68, v68, 0x3a800000, v220
	v_mul_f32_e32 v69, 0x4b800000, v68
	v_cmp_gt_f32_e32 vcc, s33, v68
	s_nop 1
	v_cndmask_b32_e32 v68, v68, v69, vcc
	v_rsq_f32_e32 v68, v68
	s_nop 0
	v_mul_f32_e32 v69, 0x45800000, v68
	v_cndmask_b32_e32 v68, v68, v69, vcc
	ds_write_b32 v0, v68 offset:3072
	v_add_f32_e32 v84, v84, v85
	v_fmamk_f32 v84, v84, 0x3a800000, v220
	v_mul_f32_e32 v85, 0x4b800000, v84
	v_cmp_gt_f32_e32 vcc, s33, v84
	s_nop 1
	v_cndmask_b32_e32 v84, v84, v85, vcc
	v_rsq_f32_e32 v84, v84
	s_nop 0
	v_mul_f32_e32 v85, 0x45800000, v84
	v_cndmask_b32_e32 v84, v84, v85, vcc
	ds_write_b32 v0, v84 offset:4096
	v_add_f32_e32 v100, v100, v101
	v_fmamk_f32 v100, v100, 0x3a800000, v220
	v_mul_f32_e32 v101, 0x4b800000, v100
	v_cmp_gt_f32_e32 vcc, s33, v100
	s_nop 1
	v_cndmask_b32_e32 v100, v100, v101, vcc
	v_rsq_f32_e32 v100, v100
	s_nop 0
	v_mul_f32_e32 v101, 0x45800000, v100
	v_cndmask_b32_e32 v100, v100, v101, vcc
	ds_write_b32 v0, v100 offset:5120
	v_add_f32_e32 v116, v116, v117
	v_fmamk_f32 v116, v116, 0x3a800000, v220
	v_mul_f32_e32 v117, 0x4b800000, v116
	v_cmp_gt_f32_e32 vcc, s33, v116
	s_nop 1
	v_cndmask_b32_e32 v116, v116, v117, vcc
	v_rsq_f32_e32 v116, v116
	s_nop 0
	v_mul_f32_e32 v117, 0x45800000, v116
	v_cndmask_b32_e32 v116, v116, v117, vcc
	ds_write_b32 v0, v116 offset:6144
	v_add_f32_e32 v132, v132, v133
	v_fmamk_f32 v132, v132, 0x3a800000, v220
	v_mul_f32_e32 v133, 0x4b800000, v132
	v_cmp_gt_f32_e32 vcc, s33, v132
	s_nop 1
	v_cndmask_b32_e32 v132, v132, v133, vcc
	v_rsq_f32_e32 v132, v132
	s_nop 0
	v_mul_f32_e32 v133, 0x45800000, v132
	v_cndmask_b32_e32 v132, v132, v133, vcc
	ds_write_b32 v0, v132 offset:7168
	v_add_f32_e32 v148, v148, v149
	v_fmamk_f32 v148, v148, 0x3a800000, v220
	v_mul_f32_e32 v149, 0x4b800000, v148
	v_cmp_gt_f32_e32 vcc, s33, v148
	s_nop 1
	v_cndmask_b32_e32 v148, v148, v149, vcc
	v_rsq_f32_e32 v148, v148
	s_nop 0
	v_mul_f32_e32 v149, 0x45800000, v148
	v_cndmask_b32_e32 v148, v148, v149, vcc
	ds_write_b32 v0, v148 offset:8192
	v_add_f32_e32 v180, v180, v181
	v_fmamk_f32 v180, v180, 0x3a800000, v220
	v_mul_f32_e32 v181, 0x4b800000, v180
	v_cmp_gt_f32_e32 vcc, s33, v180
	s_nop 1
	v_cndmask_b32_e32 v180, v180, v181, vcc
	v_rsq_f32_e32 v180, v180
	s_nop 0
	v_mul_f32_e32 v181, 0x45800000, v180
	v_cndmask_b32_e32 v180, v180, v181, vcc
	ds_write_b32 v0, v180 offset:9216
	v_add_f32_e32 v196, v196, v197
	v_fmamk_f32 v196, v196, 0x3a800000, v220
	v_mul_f32_e32 v197, 0x4b800000, v196
	v_cmp_gt_f32_e32 vcc, s33, v196
	s_nop 1
	v_cndmask_b32_e32 v196, v196, v197, vcc
	v_rsq_f32_e32 v196, v196
	s_nop 0
	v_mul_f32_e32 v197, 0x45800000, v196
	v_cndmask_b32_e32 v196, v196, v197, vcc
	ds_write_b32 v0, v196 offset:10240
.Lrs_skipw:
	s_or_b64 exec, exec, s[14:15]
	s_branch .LBB0_1088

.LBB0_1308:
	s_and_b64 vcc, exec, s[10:11]
	s_cbranch_vccz .Lnot_last_phase
	v_readlane_b32 s2, v255, 23
	s_nop 0
	s_cmp_eq_u32 s2, 3
	s_cbranch_scc0 .Lnot_last_phase
	s_endpgm
